# cache policy: the FFN hidden-activation stores of P1 and P10 (write-once streams of 369 MB each) marked non-temporal
# speedup vs baseline: 1.0060x; 1.0060x over previous
.LBB0_189:
	v_mov_b32_e32 v144, v150
	v_mov_b32_e32 v146, v1
	s_lshl_b32 s12, s52, 8
	s_add_i32 s12, s12, s66
	v_lshlrev_b32_e32 v142, 4, v146
	v_add_u32_e32 v146, s12, v146
	v_ashrrev_i32_e32 v147, 31, v146
	v_lshl_add_u64 v[148:149], v[146:147], 2, s[6:7]
	global_load_dword v147, v[148:149], off
	global_load_dword v180, v[148:149], off offset:64
	global_load_dword v181, v[148:149], off offset:128
	global_load_dword v182, v[148:149], off offset:192
	global_load_dword v183, v[148:149], off offset:512
	global_load_dword v184, v[148:149], off offset:576
	global_load_dword v185, v[148:149], off offset:640
	global_load_dword v186, v[148:149], off offset:704
	s_lshl_b32 s12, s14, 1
	s_ashr_i32 s13, s12, 31
	s_lshl_b32 s52, s52, 1
	s_ashr_i32 s53, s52, 31
	s_lshl_b64 s[12:13], s[12:13], 22
	s_add_u32 s12, s30, s12
	s_addc_u32 s13, s31, s13
	s_lshl_b64 s[14:15], s[52:53], 14
	s_add_u32 s14, s12, s14
	s_addc_u32 s15, s13, s15
	v_ashrrev_i32_e32 v143, 31, v142
	v_lshlrev_b32_e32 v144, 2, v144
	s_add_u32 s34, s14, s24
	v_ashrrev_i32_e32 v145, 31, v144
	s_addc_u32 s35, s15, s25
	v_lshlrev_b64 v[142:143], 1, v[142:143]
	v_lshlrev_b64 v[144:145], 1, v[144:145]
	s_waitcnt vmcnt(0)
	v_fmamk_f32 v147, v147, 0x3a800000, v155
	v_cmp_gt_f32_e32 vcc, s84, v147
	v_mul_f32_e32 v148, 0x4b800000, v147
	s_nop 0
	v_cndmask_b32_e32 v147, v147, v148, vcc
	v_rsq_f32_e32 v147, v147
	s_nop 0
	v_mul_f32_e32 v148, 0x45800000, v147
	v_cndmask_b32_e32 v156, v147, v148, vcc
	v_pk_mul_f32 v[126:127], v[126:127], v[156:157] op_sel_hi:[1,0]
	v_pk_mul_f32 v[122:123], v[122:123], v[156:157] op_sel_hi:[1,0]
	v_mul_f32_e32 v147, 0xbfb8aa3b, v126
	v_exp_f32_e32 v147, v147
	v_pk_mul_f32 v[124:125], v[124:125], v[156:157] op_sel_hi:[1,0]
	v_lshl_add_u64 v[148:149], s[34:35], 0, v[142:143]
	v_lshl_add_u64 v[148:149], v[148:149], 0, v[144:145]
	v_add_f32_e32 v147, 1.0, v147
	v_rcp_f32_e32 v158, v147
	v_mul_f32_e32 v147, 0xbfb8aa3b, v127
	v_exp_f32_e32 v147, v147
	v_pk_mul_f32 v[118:119], v[118:119], v[156:157] op_sel_hi:[1,0]
	v_pk_mul_f32 v[114:115], v[114:115], v[156:157] op_sel_hi:[1,0]
	v_pk_mul_f32 v[116:117], v[116:117], v[156:157] op_sel_hi:[1,0]
	v_add_f32_e32 v147, 1.0, v147
	v_rcp_f32_e32 v159, v147
	s_add_u32 s34, s14, s36
	s_addc_u32 s35, s15, s37
	s_add_u32 s14, s14, s38
	v_pk_mul_f32 v[126:127], v[126:127], v[158:159]
	s_addc_u32 s15, s15, s39
	v_pk_mul_f32 v[122:123], v[122:123], v[126:127]
	v_pk_mul_f32 v[126:127], v[128:129], v[156:157] op_sel_hi:[1,0]
	v_cvt_pk_bf16_f32 v122, v122, v123
	v_mul_f32_e32 v128, 0xbfb8aa3b, v126
	v_mul_f32_e32 v129, 0xbfb8aa3b, v127
	v_exp_f32_e32 v128, v128
	v_exp_f32_e32 v129, v129
	v_add_f32_e32 v128, 1.0, v128
	v_add_f32_e32 v129, 1.0, v129
	v_rcp_f32_e32 v128, v128
	v_rcp_f32_e32 v129, v129
	s_nop 0
	v_pk_mul_f32 v[126:127], v[126:127], v[128:129]
	s_nop 0
	v_pk_mul_f32 v[124:125], v[124:125], v[126:127]
	s_nop 0
	v_cvt_pk_bf16_f32 v123, v124, v125
	global_store_dwordx2 v[148:149], v[122:123], off nt
	v_mul_f32_e32 v122, 0xbfb8aa3b, v118
	v_mul_f32_e32 v123, 0xbfb8aa3b, v119
	v_exp_f32_e32 v122, v122
	v_exp_f32_e32 v123, v123
	v_add_f32_e32 v122, 1.0, v122
	v_add_f32_e32 v123, 1.0, v123
	v_rcp_f32_e32 v122, v122
	v_rcp_f32_e32 v123, v123
	s_nop 0
	v_pk_mul_f32 v[118:119], v[118:119], v[122:123]
	s_nop 0
	v_pk_mul_f32 v[114:115], v[114:115], v[118:119]
	v_pk_mul_f32 v[118:119], v[120:121], v[156:157] op_sel_hi:[1,0]
	s_nop 0
	v_mul_f32_e32 v120, 0xbfb8aa3b, v118
	v_mul_f32_e32 v121, 0xbfb8aa3b, v119
	v_exp_f32_e32 v120, v120
	v_exp_f32_e32 v121, v121
	v_add_f32_e32 v120, 1.0, v120
	v_add_f32_e32 v121, 1.0, v121
	v_rcp_f32_e32 v120, v120
	v_rcp_f32_e32 v121, v121
	s_nop 0
	v_pk_mul_f32 v[118:119], v[118:119], v[120:121]
	s_nop 0
	v_pk_mul_f32 v[116:117], v[116:117], v[118:119]
	v_cvt_pk_bf16_f32 v118, v114, v115
	v_cvt_pk_bf16_f32 v119, v116, v117
	v_add_co_u32_e32 v114, vcc, s85, v148
	v_add_u32_e32 v116, 16, v146
	s_nop 0
	v_addc_co_u32_e32 v115, vcc, 0, v149, vcc
	v_ashrrev_i32_e32 v117, 31, v116
	global_store_dwordx2 v[114:115], v[118:119], off nt
	v_lshl_add_u64 v[116:117], v[116:117], 2, s[6:7]
	v_fmamk_f32 v116, v180, 0x3a800000, v155
	v_cmp_gt_f32_e32 vcc, s84, v116
	v_mul_f32_e32 v117, 0x4b800000, v116
	s_nop 0
	v_cndmask_b32_e32 v116, v116, v117, vcc
	v_rsq_f32_e32 v116, v116
	s_nop 0
	v_mul_f32_e32 v117, 0x45800000, v116
	v_cndmask_b32_e32 v116, v116, v117, vcc
	v_pk_mul_f32 v[110:111], v[110:111], v[116:117] op_sel_hi:[1,0]
	s_nop 0
	v_mul_f32_e32 v117, 0xbfb8aa3b, v110
	v_exp_f32_e32 v117, v117
	s_nop 0
	v_add_f32_e32 v117, 1.0, v117
	v_rcp_f32_e32 v118, v117
	v_mul_f32_e32 v117, 0xbfb8aa3b, v111
	v_exp_f32_e32 v117, v117
	s_nop 0
	v_add_f32_e32 v117, 1.0, v117
	v_rcp_f32_e32 v119, v117
	v_pk_mul_f32 v[106:107], v[106:107], v[116:117] op_sel_hi:[1,0]
	v_pk_mul_f32 v[108:109], v[108:109], v[116:117] op_sel_hi:[1,0]
	v_pk_mul_f32 v[102:103], v[102:103], v[116:117] op_sel_hi:[1,0]
	v_pk_mul_f32 v[110:111], v[110:111], v[118:119]
	v_pk_mul_f32 v[98:99], v[98:99], v[116:117] op_sel_hi:[1,0]
	v_pk_mul_f32 v[106:107], v[106:107], v[110:111]
	v_pk_mul_f32 v[110:111], v[112:113], v[116:117] op_sel_hi:[1,0]
	v_cvt_pk_bf16_f32 v106, v106, v107
	v_mul_f32_e32 v112, 0xbfb8aa3b, v110
	v_mul_f32_e32 v113, 0xbfb8aa3b, v111
	v_exp_f32_e32 v112, v112
	v_exp_f32_e32 v113, v113
	v_pk_mul_f32 v[100:101], v[100:101], v[116:117] op_sel_hi:[1,0]
	v_add_f32_e32 v112, 1.0, v112
	v_add_f32_e32 v113, 1.0, v113
	v_rcp_f32_e32 v112, v112
	v_rcp_f32_e32 v113, v113
	s_nop 0
	v_pk_mul_f32 v[110:111], v[110:111], v[112:113]
	s_nop 0
	v_pk_mul_f32 v[108:109], v[108:109], v[110:111]
	s_nop 0
	v_cvt_pk_bf16_f32 v107, v108, v109
	global_store_dwordx2 v[148:149], v[106:107], off offset:2048 nt
	v_mul_f32_e32 v106, 0xbfb8aa3b, v102
	v_mul_f32_e32 v107, 0xbfb8aa3b, v103
	v_exp_f32_e32 v106, v106
	v_exp_f32_e32 v107, v107
	v_add_f32_e32 v106, 1.0, v106
	v_add_f32_e32 v107, 1.0, v107
	v_rcp_f32_e32 v106, v106
	v_rcp_f32_e32 v107, v107
	s_nop 0
	v_pk_mul_f32 v[102:103], v[102:103], v[106:107]
	s_nop 0
	v_pk_mul_f32 v[98:99], v[98:99], v[102:103]
	v_pk_mul_f32 v[102:103], v[104:105], v[116:117] op_sel_hi:[1,0]
	v_cvt_pk_bf16_f32 v98, v98, v99
	v_mul_f32_e32 v104, 0xbfb8aa3b, v102
	v_mul_f32_e32 v105, 0xbfb8aa3b, v103
	v_exp_f32_e32 v104, v104
	v_exp_f32_e32 v105, v105
	v_add_f32_e32 v104, 1.0, v104
	v_add_f32_e32 v105, 1.0, v105
	v_rcp_f32_e32 v104, v104
	v_rcp_f32_e32 v105, v105
	s_nop 0
	v_pk_mul_f32 v[102:103], v[102:103], v[104:105]
	s_nop 0
	v_pk_mul_f32 v[100:101], v[100:101], v[102:103]
	s_nop 0
	v_cvt_pk_bf16_f32 v99, v100, v101
	global_store_dwordx2 v[114:115], v[98:99], off offset:2048 nt
	v_add_u32_e32 v98, 32, v146
	v_ashrrev_i32_e32 v99, 31, v98
	v_lshl_add_u64 v[98:99], v[98:99], 2, s[6:7]
	v_lshl_add_u64 v[100:101], s[34:35], 0, v[142:143]
	v_lshl_add_u64 v[100:101], v[100:101], 0, v[144:145]
	s_mov_b64 s[34:35], -1
	v_fmamk_f32 v98, v181, 0x3a800000, v155
	v_cmp_gt_f32_e32 vcc, s84, v98
	v_mul_f32_e32 v99, 0x4b800000, v98
	s_nop 0
	v_cndmask_b32_e32 v98, v98, v99, vcc
	v_rsq_f32_e32 v98, v98
	s_nop 0
	v_mul_f32_e32 v99, 0x45800000, v98
	v_cndmask_b32_e32 v98, v98, v99, vcc
	v_pk_mul_f32 v[94:95], v[94:95], v[98:99] op_sel_hi:[1,0]
	s_nop 0
	v_mul_f32_e32 v99, 0xbfb8aa3b, v94
	v_exp_f32_e32 v99, v99
	s_nop 0
	v_add_f32_e32 v99, 1.0, v99
	v_rcp_f32_e32 v102, v99
	v_mul_f32_e32 v99, 0xbfb8aa3b, v95
	v_exp_f32_e32 v99, v99
	s_nop 0
	v_add_f32_e32 v99, 1.0, v99
	v_rcp_f32_e32 v103, v99
	v_pk_mul_f32 v[90:91], v[90:91], v[98:99] op_sel_hi:[1,0]
	v_pk_mul_f32 v[92:93], v[92:93], v[98:99] op_sel_hi:[1,0]
	v_pk_mul_f32 v[86:87], v[86:87], v[98:99] op_sel_hi:[1,0]
	v_pk_mul_f32 v[94:95], v[94:95], v[102:103]
	v_pk_mul_f32 v[82:83], v[82:83], v[98:99] op_sel_hi:[1,0]
	v_pk_mul_f32 v[90:91], v[90:91], v[94:95]
	v_pk_mul_f32 v[94:95], v[96:97], v[98:99] op_sel_hi:[1,0]
	v_cvt_pk_bf16_f32 v90, v90, v91
	v_mul_f32_e32 v96, 0xbfb8aa3b, v94
	v_mul_f32_e32 v97, 0xbfb8aa3b, v95
	v_exp_f32_e32 v96, v96
	v_exp_f32_e32 v97, v97
	v_pk_mul_f32 v[84:85], v[84:85], v[98:99] op_sel_hi:[1,0]
	v_add_f32_e32 v96, 1.0, v96
	v_add_f32_e32 v97, 1.0, v97
	v_rcp_f32_e32 v96, v96
	v_rcp_f32_e32 v97, v97
	s_nop 0
	v_pk_mul_f32 v[94:95], v[94:95], v[96:97]
	s_nop 0
	v_pk_mul_f32 v[92:93], v[92:93], v[94:95]
	s_nop 0
	v_cvt_pk_bf16_f32 v91, v92, v93
	global_store_dwordx2 v[100:101], v[90:91], off nt
	v_mul_f32_e32 v90, 0xbfb8aa3b, v86
	v_mul_f32_e32 v91, 0xbfb8aa3b, v87
	v_exp_f32_e32 v90, v90
	v_exp_f32_e32 v91, v91
	v_add_f32_e32 v90, 1.0, v90
	v_add_f32_e32 v91, 1.0, v91
	v_rcp_f32_e32 v90, v90
	v_rcp_f32_e32 v91, v91
	s_nop 0
	v_pk_mul_f32 v[86:87], v[86:87], v[90:91]
	s_nop 0
	v_pk_mul_f32 v[82:83], v[82:83], v[86:87]
	v_pk_mul_f32 v[86:87], v[88:89], v[98:99] op_sel_hi:[1,0]
	v_cvt_pk_bf16_f32 v82, v82, v83
	v_mul_f32_e32 v88, 0xbfb8aa3b, v86
	v_mul_f32_e32 v89, 0xbfb8aa3b, v87
	v_exp_f32_e32 v88, v88
	v_exp_f32_e32 v89, v89
	v_add_f32_e32 v88, 1.0, v88
	v_add_f32_e32 v89, 1.0, v89
	v_rcp_f32_e32 v88, v88
	v_rcp_f32_e32 v89, v89
	s_nop 0
	v_pk_mul_f32 v[86:87], v[86:87], v[88:89]
	s_nop 0
	v_pk_mul_f32 v[84:85], v[84:85], v[86:87]
	s_nop 0
	v_cvt_pk_bf16_f32 v83, v84, v85
	v_add_co_u32_e32 v84, vcc, s85, v100
	s_nop 1
	v_addc_co_u32_e32 v85, vcc, 0, v101, vcc
	global_store_dwordx2 v[84:85], v[82:83], off nt
	v_add_u32_e32 v82, 48, v146
	v_ashrrev_i32_e32 v83, 31, v82
	v_lshl_add_u64 v[82:83], v[82:83], 2, s[6:7]
	v_lshl_add_u64 v[84:85], s[14:15], 0, v[142:143]
	v_lshl_add_u64 v[84:85], v[84:85], 0, v[144:145]
	s_or_b32 s14, s52, 1
	s_ashr_i32 s15, s14, 31
	s_lshl_b64 s[14:15], s[14:15], 14
	s_add_u32 s12, s12, s14
	s_addc_u32 s13, s13, s15
	s_add_u32 s14, s12, s24
	s_addc_u32 s15, s13, s25
	v_fmamk_f32 v82, v182, 0x3a800000, v155
	v_cmp_gt_f32_e32 vcc, s84, v82
	v_mul_f32_e32 v83, 0x4b800000, v82
	s_nop 0
	v_cndmask_b32_e32 v82, v82, v83, vcc
	v_rsq_f32_e32 v82, v82
	s_nop 0
	v_mul_f32_e32 v83, 0x45800000, v82
	v_cndmask_b32_e32 v82, v82, v83, vcc
	v_pk_mul_f32 v[78:79], v[78:79], v[82:83] op_sel_hi:[1,0]
	s_nop 0
	v_mul_f32_e32 v83, 0xbfb8aa3b, v78
	v_exp_f32_e32 v83, v83
	s_nop 0
	v_add_f32_e32 v83, 1.0, v83
	v_rcp_f32_e32 v86, v83
	v_mul_f32_e32 v83, 0xbfb8aa3b, v79
	v_exp_f32_e32 v83, v83
	s_nop 0
	v_add_f32_e32 v83, 1.0, v83
	v_rcp_f32_e32 v87, v83
	v_pk_mul_f32 v[74:75], v[74:75], v[82:83] op_sel_hi:[1,0]
	v_pk_mul_f32 v[76:77], v[76:77], v[82:83] op_sel_hi:[1,0]
	v_pk_mul_f32 v[70:71], v[70:71], v[82:83] op_sel_hi:[1,0]
	v_pk_mul_f32 v[78:79], v[78:79], v[86:87]
	v_pk_mul_f32 v[66:67], v[66:67], v[82:83] op_sel_hi:[1,0]
	v_pk_mul_f32 v[74:75], v[74:75], v[78:79]
	v_pk_mul_f32 v[78:79], v[80:81], v[82:83] op_sel_hi:[1,0]
	v_cvt_pk_bf16_f32 v74, v74, v75
	v_mul_f32_e32 v80, 0xbfb8aa3b, v78
	v_mul_f32_e32 v81, 0xbfb8aa3b, v79
	v_exp_f32_e32 v80, v80
	v_exp_f32_e32 v81, v81
	v_pk_mul_f32 v[68:69], v[68:69], v[82:83] op_sel_hi:[1,0]
	v_add_f32_e32 v80, 1.0, v80
	v_add_f32_e32 v81, 1.0, v81
	v_rcp_f32_e32 v80, v80
	v_rcp_f32_e32 v81, v81
	s_nop 0
	v_pk_mul_f32 v[78:79], v[78:79], v[80:81]
	s_nop 0
	v_pk_mul_f32 v[76:77], v[76:77], v[78:79]
	s_nop 0
	v_cvt_pk_bf16_f32 v75, v76, v77
	global_store_dwordx2 v[84:85], v[74:75], off nt
	v_mul_f32_e32 v74, 0xbfb8aa3b, v70
	v_mul_f32_e32 v75, 0xbfb8aa3b, v71
	v_exp_f32_e32 v74, v74
	v_exp_f32_e32 v75, v75
	v_add_f32_e32 v74, 1.0, v74
	v_add_f32_e32 v75, 1.0, v75
	v_rcp_f32_e32 v74, v74
	v_rcp_f32_e32 v75, v75
	s_nop 0
	v_pk_mul_f32 v[70:71], v[70:71], v[74:75]
	s_nop 0
	v_pk_mul_f32 v[66:67], v[66:67], v[70:71]
	v_pk_mul_f32 v[70:71], v[72:73], v[82:83] op_sel_hi:[1,0]
	v_cvt_pk_bf16_f32 v66, v66, v67
	v_mul_f32_e32 v72, 0xbfb8aa3b, v70
	v_mul_f32_e32 v73, 0xbfb8aa3b, v71
	v_exp_f32_e32 v72, v72
	v_exp_f32_e32 v73, v73
	v_add_f32_e32 v72, 1.0, v72
	v_add_f32_e32 v73, 1.0, v73
	v_rcp_f32_e32 v72, v72
	v_rcp_f32_e32 v73, v73
	s_nop 0
	v_pk_mul_f32 v[70:71], v[70:71], v[72:73]
	s_nop 0
	v_pk_mul_f32 v[68:69], v[68:69], v[70:71]
	s_nop 0
	v_cvt_pk_bf16_f32 v67, v68, v69
	v_add_co_u32_e32 v68, vcc, s85, v84
	s_nop 1
	v_addc_co_u32_e32 v69, vcc, 0, v85, vcc
	global_store_dwordx2 v[68:69], v[66:67], off nt
	v_add_u32_e32 v66, 0x80, v146
	v_ashrrev_i32_e32 v67, 31, v66
	v_lshl_add_u64 v[66:67], v[66:67], 2, s[6:7]
	v_fmamk_f32 v66, v183, 0x3a800000, v155
	v_cmp_gt_f32_e32 vcc, s84, v66
	v_mul_f32_e32 v67, 0x4b800000, v66
	s_nop 0
	v_cndmask_b32_e32 v66, v66, v67, vcc
	v_rsq_f32_e32 v66, v66
	s_nop 0
	v_mul_f32_e32 v67, 0x45800000, v66
	v_cndmask_b32_e32 v68, v66, v67, vcc
	v_pk_mul_f32 v[62:63], v[62:63], v[68:69] op_sel_hi:[1,0]
	v_lshl_add_u64 v[66:67], s[14:15], 0, v[142:143]
	v_mul_f32_e32 v69, 0xbfb8aa3b, v62
	v_exp_f32_e32 v69, v69
	v_lshl_add_u64 v[66:67], v[66:67], 0, v[144:145]
	s_add_u32 s14, s12, s36
	s_addc_u32 s15, s13, s37
	v_add_f32_e32 v69, 1.0, v69
	v_rcp_f32_e32 v70, v69
	v_mul_f32_e32 v69, 0xbfb8aa3b, v63
	v_exp_f32_e32 v69, v69
	s_add_u32 s12, s12, s38
	s_addc_u32 s13, s13, s39
	v_add_f32_e32 v69, 1.0, v69
	v_rcp_f32_e32 v71, v69
	v_pk_mul_f32 v[58:59], v[58:59], v[68:69] op_sel_hi:[1,0]
	v_pk_mul_f32 v[60:61], v[60:61], v[68:69] op_sel_hi:[1,0]
	v_pk_mul_f32 v[54:55], v[54:55], v[68:69] op_sel_hi:[1,0]
	v_pk_mul_f32 v[62:63], v[62:63], v[70:71]
	v_pk_mul_f32 v[50:51], v[50:51], v[68:69] op_sel_hi:[1,0]
	v_pk_mul_f32 v[58:59], v[58:59], v[62:63]
	v_pk_mul_f32 v[62:63], v[64:65], v[68:69] op_sel_hi:[1,0]
	v_cvt_pk_bf16_f32 v58, v58, v59
	v_mul_f32_e32 v64, 0xbfb8aa3b, v62
	v_mul_f32_e32 v65, 0xbfb8aa3b, v63
	v_exp_f32_e32 v64, v64
	v_exp_f32_e32 v65, v65
	v_pk_mul_f32 v[52:53], v[52:53], v[68:69] op_sel_hi:[1,0]
	v_add_f32_e32 v64, 1.0, v64
	v_add_f32_e32 v65, 1.0, v65
	v_rcp_f32_e32 v64, v64
	v_rcp_f32_e32 v65, v65
	s_nop 0
	v_pk_mul_f32 v[62:63], v[62:63], v[64:65]
	s_nop 0
	v_pk_mul_f32 v[60:61], v[60:61], v[62:63]
	s_nop 0
	v_cvt_pk_bf16_f32 v59, v60, v61
	global_store_dwordx2 v[66:67], v[58:59], off nt
	v_mul_f32_e32 v58, 0xbfb8aa3b, v54
	v_mul_f32_e32 v59, 0xbfb8aa3b, v55
	v_exp_f32_e32 v58, v58
	v_exp_f32_e32 v59, v59
	v_add_f32_e32 v58, 1.0, v58
	v_add_f32_e32 v59, 1.0, v59
	v_rcp_f32_e32 v58, v58
	v_rcp_f32_e32 v59, v59
	s_nop 0
	v_pk_mul_f32 v[54:55], v[54:55], v[58:59]
	s_nop 0
	v_pk_mul_f32 v[50:51], v[50:51], v[54:55]
	v_pk_mul_f32 v[54:55], v[56:57], v[68:69] op_sel_hi:[1,0]
	s_nop 0
	v_mul_f32_e32 v56, 0xbfb8aa3b, v54
	v_mul_f32_e32 v57, 0xbfb8aa3b, v55
	v_exp_f32_e32 v56, v56
	v_exp_f32_e32 v57, v57
	v_add_f32_e32 v56, 1.0, v56
	v_add_f32_e32 v57, 1.0, v57
	v_rcp_f32_e32 v56, v56
	v_rcp_f32_e32 v57, v57
	s_nop 0
	v_pk_mul_f32 v[54:55], v[54:55], v[56:57]
	s_nop 0
	v_pk_mul_f32 v[52:53], v[52:53], v[54:55]
	v_cvt_pk_bf16_f32 v54, v50, v51
	v_cvt_pk_bf16_f32 v55, v52, v53
	v_add_co_u32_e32 v50, vcc, s85, v66
	v_add_u32_e32 v52, 0x90, v146
	s_nop 0
	v_addc_co_u32_e32 v51, vcc, 0, v67, vcc
	v_ashrrev_i32_e32 v53, 31, v52
	global_store_dwordx2 v[50:51], v[54:55], off nt
	v_lshl_add_u64 v[52:53], v[52:53], 2, s[6:7]
	v_fmamk_f32 v52, v184, 0x3a800000, v155
	v_cmp_gt_f32_e32 vcc, s84, v52
	v_mul_f32_e32 v53, 0x4b800000, v52
	s_nop 0
	v_cndmask_b32_e32 v52, v52, v53, vcc
	v_rsq_f32_e32 v52, v52
	s_nop 0
	v_mul_f32_e32 v53, 0x45800000, v52
	v_cndmask_b32_e32 v52, v52, v53, vcc
	v_pk_mul_f32 v[46:47], v[46:47], v[52:53] op_sel_hi:[1,0]
	s_nop 0
	v_mul_f32_e32 v53, 0xbfb8aa3b, v46
	v_exp_f32_e32 v53, v53
	s_nop 0
	v_add_f32_e32 v53, 1.0, v53
	v_rcp_f32_e32 v54, v53
	v_mul_f32_e32 v53, 0xbfb8aa3b, v47
	v_exp_f32_e32 v53, v53
	s_nop 0
	v_add_f32_e32 v53, 1.0, v53
	v_rcp_f32_e32 v55, v53
	v_pk_mul_f32 v[42:43], v[42:43], v[52:53] op_sel_hi:[1,0]
	v_pk_mul_f32 v[44:45], v[44:45], v[52:53] op_sel_hi:[1,0]
	v_pk_mul_f32 v[38:39], v[38:39], v[52:53] op_sel_hi:[1,0]
	v_pk_mul_f32 v[46:47], v[46:47], v[54:55]
	v_pk_mul_f32 v[34:35], v[34:35], v[52:53] op_sel_hi:[1,0]
	v_pk_mul_f32 v[42:43], v[42:43], v[46:47]
	v_pk_mul_f32 v[46:47], v[48:49], v[52:53] op_sel_hi:[1,0]
	v_cvt_pk_bf16_f32 v42, v42, v43
	v_mul_f32_e32 v48, 0xbfb8aa3b, v46
	v_mul_f32_e32 v49, 0xbfb8aa3b, v47
	v_exp_f32_e32 v48, v48
	v_exp_f32_e32 v49, v49
	v_pk_mul_f32 v[36:37], v[36:37], v[52:53] op_sel_hi:[1,0]
	v_add_f32_e32 v48, 1.0, v48
	v_add_f32_e32 v49, 1.0, v49
	v_rcp_f32_e32 v48, v48
	v_rcp_f32_e32 v49, v49
	s_nop 0
	v_pk_mul_f32 v[46:47], v[46:47], v[48:49]
	s_nop 0
	v_pk_mul_f32 v[44:45], v[44:45], v[46:47]
	s_nop 0
	v_cvt_pk_bf16_f32 v43, v44, v45
	global_store_dwordx2 v[66:67], v[42:43], off offset:2048 nt
	v_mul_f32_e32 v42, 0xbfb8aa3b, v38
	v_mul_f32_e32 v43, 0xbfb8aa3b, v39
	v_exp_f32_e32 v42, v42
	v_exp_f32_e32 v43, v43
	v_add_f32_e32 v42, 1.0, v42
	v_add_f32_e32 v43, 1.0, v43
	v_rcp_f32_e32 v42, v42
	v_rcp_f32_e32 v43, v43
	s_nop 0
	v_pk_mul_f32 v[38:39], v[38:39], v[42:43]
	s_nop 0
	v_pk_mul_f32 v[34:35], v[34:35], v[38:39]
	v_pk_mul_f32 v[38:39], v[40:41], v[52:53] op_sel_hi:[1,0]
	v_cvt_pk_bf16_f32 v34, v34, v35
	v_mul_f32_e32 v40, 0xbfb8aa3b, v38
	v_mul_f32_e32 v41, 0xbfb8aa3b, v39
	v_exp_f32_e32 v40, v40
	v_exp_f32_e32 v41, v41
	v_add_f32_e32 v40, 1.0, v40
	v_add_f32_e32 v41, 1.0, v41
	v_rcp_f32_e32 v40, v40
	v_rcp_f32_e32 v41, v41
	s_nop 0
	v_pk_mul_f32 v[38:39], v[38:39], v[40:41]
	s_nop 0
	v_pk_mul_f32 v[36:37], v[36:37], v[38:39]
	s_nop 0
	v_cvt_pk_bf16_f32 v35, v36, v37
	global_store_dwordx2 v[50:51], v[34:35], off offset:2048 nt
	v_add_u32_e32 v34, 0xa0, v146
	v_ashrrev_i32_e32 v35, 31, v34
	v_lshl_add_u64 v[34:35], v[34:35], 2, s[6:7]
	v_lshl_add_u64 v[36:37], s[14:15], 0, v[142:143]
	v_lshl_add_u64 v[36:37], v[36:37], 0, v[144:145]
	v_fmamk_f32 v34, v185, 0x3a800000, v155
	v_cmp_gt_f32_e32 vcc, s84, v34
	v_mul_f32_e32 v35, 0x4b800000, v34
	s_nop 0
	v_cndmask_b32_e32 v34, v34, v35, vcc
	v_rsq_f32_e32 v34, v34
	s_nop 0
	v_mul_f32_e32 v35, 0x45800000, v34
	v_cndmask_b32_e32 v34, v34, v35, vcc
	v_pk_mul_f32 v[30:31], v[30:31], v[34:35] op_sel_hi:[1,0]
	s_nop 0
	v_mul_f32_e32 v35, 0xbfb8aa3b, v30
	v_exp_f32_e32 v35, v35
	s_nop 0
	v_add_f32_e32 v35, 1.0, v35
	v_rcp_f32_e32 v38, v35
	v_mul_f32_e32 v35, 0xbfb8aa3b, v31
	v_exp_f32_e32 v35, v35
	s_nop 0
	v_add_f32_e32 v35, 1.0, v35
	v_rcp_f32_e32 v39, v35
	v_pk_mul_f32 v[26:27], v[26:27], v[34:35] op_sel_hi:[1,0]
	v_pk_mul_f32 v[28:29], v[28:29], v[34:35] op_sel_hi:[1,0]
	v_pk_mul_f32 v[22:23], v[22:23], v[34:35] op_sel_hi:[1,0]
	v_pk_mul_f32 v[30:31], v[30:31], v[38:39]
	v_pk_mul_f32 v[18:19], v[18:19], v[34:35] op_sel_hi:[1,0]
	v_pk_mul_f32 v[26:27], v[26:27], v[30:31]
	v_pk_mul_f32 v[30:31], v[32:33], v[34:35] op_sel_hi:[1,0]
	v_cvt_pk_bf16_f32 v26, v26, v27
	v_mul_f32_e32 v32, 0xbfb8aa3b, v30
	v_mul_f32_e32 v33, 0xbfb8aa3b, v31
	v_exp_f32_e32 v32, v32
	v_exp_f32_e32 v33, v33
	v_pk_mul_f32 v[20:21], v[20:21], v[34:35] op_sel_hi:[1,0]
	v_add_f32_e32 v32, 1.0, v32
	v_add_f32_e32 v33, 1.0, v33
	v_rcp_f32_e32 v32, v32
	v_rcp_f32_e32 v33, v33
	s_nop 0
	v_pk_mul_f32 v[30:31], v[30:31], v[32:33]
	s_nop 0
	v_pk_mul_f32 v[28:29], v[28:29], v[30:31]
	s_nop 0
	v_cvt_pk_bf16_f32 v27, v28, v29
	global_store_dwordx2 v[36:37], v[26:27], off nt
	v_mul_f32_e32 v26, 0xbfb8aa3b, v22
	v_mul_f32_e32 v27, 0xbfb8aa3b, v23
	v_exp_f32_e32 v26, v26
	v_exp_f32_e32 v27, v27
	v_add_f32_e32 v26, 1.0, v26
	v_add_f32_e32 v27, 1.0, v27
	v_rcp_f32_e32 v26, v26
	v_rcp_f32_e32 v27, v27
	s_nop 0
	v_pk_mul_f32 v[22:23], v[22:23], v[26:27]
	s_nop 0
	v_pk_mul_f32 v[18:19], v[18:19], v[22:23]
	v_pk_mul_f32 v[22:23], v[24:25], v[34:35] op_sel_hi:[1,0]
	v_cvt_pk_bf16_f32 v18, v18, v19
	v_mul_f32_e32 v24, 0xbfb8aa3b, v22
	v_mul_f32_e32 v25, 0xbfb8aa3b, v23
	v_exp_f32_e32 v24, v24
	v_exp_f32_e32 v25, v25
	v_add_f32_e32 v24, 1.0, v24
	v_add_f32_e32 v25, 1.0, v25
	v_rcp_f32_e32 v24, v24
	v_rcp_f32_e32 v25, v25
	s_nop 0
	v_pk_mul_f32 v[22:23], v[22:23], v[24:25]
	s_nop 0
	v_pk_mul_f32 v[20:21], v[20:21], v[22:23]
	s_nop 0
	v_cvt_pk_bf16_f32 v19, v20, v21
	v_add_co_u32_e32 v20, vcc, s85, v36
	s_nop 1
	v_addc_co_u32_e32 v21, vcc, 0, v37, vcc
	global_store_dwordx2 v[20:21], v[18:19], off nt
	v_add_u32_e32 v18, 0xb0, v146
	v_ashrrev_i32_e32 v19, 31, v18
	v_lshl_add_u64 v[18:19], v[18:19], 2, s[6:7]
	v_lshl_add_u64 v[20:21], s[12:13], 0, v[142:143]
	v_lshl_add_u64 v[20:21], v[20:21], 0, v[144:145]
	v_fmamk_f32 v18, v186, 0x3a800000, v155
	v_cmp_gt_f32_e32 vcc, s84, v18
	v_mul_f32_e32 v19, 0x4b800000, v18
	s_nop 0
	v_cndmask_b32_e32 v18, v18, v19, vcc
	v_rsq_f32_e32 v18, v18
	s_nop 0
	v_mul_f32_e32 v19, 0x45800000, v18
	v_cndmask_b32_e32 v18, v18, v19, vcc
	v_pk_mul_f32 v[14:15], v[14:15], v[18:19] op_sel_hi:[1,0]
	s_nop 0
	v_mul_f32_e32 v19, 0xbfb8aa3b, v14
	v_exp_f32_e32 v19, v19
	s_nop 0
	v_add_f32_e32 v19, 1.0, v19
	v_rcp_f32_e32 v22, v19
	v_mul_f32_e32 v19, 0xbfb8aa3b, v15
	v_exp_f32_e32 v19, v19
	s_nop 0
	v_add_f32_e32 v19, 1.0, v19
	v_rcp_f32_e32 v23, v19
	v_pk_mul_f32 v[10:11], v[10:11], v[18:19] op_sel_hi:[1,0]
	v_pk_mul_f32 v[12:13], v[12:13], v[18:19] op_sel_hi:[1,0]
	v_pk_mul_f32 v[6:7], v[6:7], v[18:19] op_sel_hi:[1,0]
	v_pk_mul_f32 v[14:15], v[14:15], v[22:23]
	v_pk_mul_f32 v[2:3], v[2:3], v[18:19] op_sel_hi:[1,0]
	v_pk_mul_f32 v[10:11], v[10:11], v[14:15]
	v_pk_mul_f32 v[14:15], v[16:17], v[18:19] op_sel_hi:[1,0]
	v_cvt_pk_bf16_f32 v10, v10, v11
	v_mul_f32_e32 v16, 0xbfb8aa3b, v14
	v_mul_f32_e32 v17, 0xbfb8aa3b, v15
	v_exp_f32_e32 v16, v16
	v_exp_f32_e32 v17, v17
	v_pk_mul_f32 v[4:5], v[4:5], v[18:19] op_sel_hi:[1,0]
	v_add_f32_e32 v16, 1.0, v16
	v_add_f32_e32 v17, 1.0, v17
	v_rcp_f32_e32 v16, v16
	v_rcp_f32_e32 v17, v17
	s_nop 0
	v_pk_mul_f32 v[14:15], v[14:15], v[16:17]
	s_nop 0
	v_pk_mul_f32 v[12:13], v[12:13], v[14:15]
	s_nop 0
	v_cvt_pk_bf16_f32 v11, v12, v13
	global_store_dwordx2 v[20:21], v[10:11], off nt
	v_mul_f32_e32 v10, 0xbfb8aa3b, v6
	v_mul_f32_e32 v11, 0xbfb8aa3b, v7
	v_exp_f32_e32 v10, v10
	v_exp_f32_e32 v11, v11
	v_add_f32_e32 v10, 1.0, v10
	v_add_f32_e32 v11, 1.0, v11
	v_rcp_f32_e32 v10, v10
	v_rcp_f32_e32 v11, v11
	s_nop 0
	v_pk_mul_f32 v[6:7], v[6:7], v[10:11]
	s_nop 0
	v_pk_mul_f32 v[2:3], v[2:3], v[6:7]
	v_pk_mul_f32 v[6:7], v[8:9], v[18:19] op_sel_hi:[1,0]
	v_cvt_pk_bf16_f32 v2, v2, v3
	v_mul_f32_e32 v8, 0xbfb8aa3b, v6
	v_mul_f32_e32 v9, 0xbfb8aa3b, v7
	v_exp_f32_e32 v8, v8
	v_exp_f32_e32 v9, v9
	v_add_f32_e32 v8, 1.0, v8
	v_add_f32_e32 v9, 1.0, v9
	v_rcp_f32_e32 v8, v8
	v_rcp_f32_e32 v9, v9
	s_nop 0
	v_pk_mul_f32 v[6:7], v[6:7], v[8:9]
	s_nop 0
	v_pk_mul_f32 v[4:5], v[4:5], v[6:7]
	s_nop 0
	v_cvt_pk_bf16_f32 v3, v4, v5
	v_add_co_u32_e32 v4, vcc, 0x400000, v20
	s_nop 1
	v_addc_co_u32_e32 v5, vcc, 0, v21, vcc
	s_andn2_b64 vcc, exec, s[4:5]
	global_store_dwordx2 v[4:5], v[2:3], off nt
	s_cbranch_vccnz .LBB0_182
	s_andn2_b64 vcc, exec, s[0:1]
	s_cbranch_vccnz .LBB0_181
	s_barrier
	s_branch .LBB0_181

.LBB0_1392:
	s_lshl_b32 s12, s0, 8
	v_mov_b32_e32 v144, v148
	v_mov_b32_e32 v145, v1
	s_add_i32 s12, s12, s51
	s_lshl_b32 s34, s1, 1
	v_add_u32_e32 v146, s12, v145
	v_ashrrev_i32_e32 v147, 31, v146
	v_lshl_add_u64 v[142:143], v[146:147], 2, s[10:11]
	global_load_dword v147, v[142:143], off
	global_load_dword v182, v[142:143], off offset:64
	global_load_dword v183, v[142:143], off offset:128
	global_load_dword v184, v[142:143], off offset:192
	global_load_dword v185, v[142:143], off offset:512
	global_load_dword v186, v[142:143], off offset:576
	global_load_dword v187, v[142:143], off offset:640
	global_load_dword v188, v[142:143], off offset:704
	s_lshl_b32 s12, s0, 1
	s_ashr_i32 s35, s34, 31
	s_ashr_i32 s13, s12, 31
	s_lshl_b64 s[0:1], s[34:35], 22
	s_add_u32 s29, s3, s0
	s_addc_u32 s31, s50, s1
	s_lshl_b64 s[0:1], s[12:13], 14
	s_add_u32 s13, s29, s0
	v_lshlrev_b32_e32 v142, 4, v145
	s_addc_u32 s34, s31, s1
	v_lshlrev_b32_e32 v144, 2, v144
	v_ashrrev_i32_e32 v143, 31, v142
	s_add_u32 s0, s13, s22
	v_ashrrev_i32_e32 v145, 31, v144
	v_lshlrev_b64 v[142:143], 1, v[142:143]
	s_addc_u32 s1, s34, s23
	v_lshlrev_b64 v[144:145], 1, v[144:145]
	v_lshl_add_u64 v[156:157], s[0:1], 0, v[142:143]
	v_add_u32_e32 v154, 16, v146
	v_lshl_add_u64 v[156:157], v[156:157], 0, v[144:145]
	v_ashrrev_i32_e32 v155, 31, v154
	v_lshl_add_u64 v[154:155], v[154:155], 2, s[10:11]
	s_waitcnt vmcnt(0)
	v_fmamk_f32 v147, v147, 0x3a800000, v153
	v_mul_f32_e32 v158, 0x4b800000, v147
	v_cmp_gt_f32_e32 vcc, s57, v147
	s_nop 1
	v_cndmask_b32_e32 v147, v147, v158, vcc
	v_rsq_f32_e32 v147, v147
	v_add_co_u32_e64 v158, s[0:1], s58, v156
	v_mul_f32_e32 v160, 0x45800000, v147
	v_cndmask_b32_e32 v160, v147, v160, vcc
	v_pk_mul_f32 v[126:127], v[126:127], v[160:161] op_sel_hi:[1,0]
	v_pk_mul_f32 v[128:129], v[128:129], v[160:161] op_sel_hi:[1,0]
	v_pk_mul_f32 v[122:123], v[122:123], v[160:161] op_sel_hi:[1,0]
	v_pk_mul_f32 v[124:125], v[124:125], v[160:161] op_sel_hi:[1,0]
	v_pk_mul_f32 v[118:119], v[118:119], v[160:161] op_sel_hi:[1,0]
	v_pk_mul_f32 v[114:115], v[114:115], v[160:161] op_sel_hi:[1,0]
	v_pk_mul_f32 v[120:121], v[120:121], v[160:161] op_sel_hi:[1,0]
	v_pk_mul_f32 v[116:117], v[116:117], v[160:161] op_sel_hi:[1,0]
	v_mul_f32_e32 v147, 0xbfb8aa3b, v126
	v_mul_f32_e32 v160, 0xbfb8aa3b, v127
	v_mul_f32_e32 v161, 0xbfb8aa3b, v128
	v_mul_f32_e32 v162, 0xbfb8aa3b, v129
	v_mul_f32_e32 v163, 0xbfb8aa3b, v118
	v_mul_f32_e32 v164, 0xbfb8aa3b, v119
	v_mul_f32_e32 v165, 0xbfb8aa3b, v120
	v_mul_f32_e32 v166, 0xbfb8aa3b, v121
	v_exp_f32_e32 v147, v147
	v_exp_f32_e32 v160, v160
	v_exp_f32_e32 v161, v161
	v_exp_f32_e32 v162, v162
	v_exp_f32_e32 v163, v163
	v_exp_f32_e32 v164, v164
	v_exp_f32_e32 v165, v165
	v_exp_f32_e32 v166, v166
	v_add_f32_e32 v147, 1.0, v147
	v_add_f32_e32 v167, 1.0, v160
	v_add_f32_e32 v168, 1.0, v161
	v_add_f32_e32 v169, 1.0, v162
	v_add_f32_e32 v170, 1.0, v163
	v_add_f32_e32 v171, 1.0, v164
	v_add_f32_e32 v172, 1.0, v165
	v_add_f32_e32 v173, 1.0, v166
	v_rcp_f32_e32 v160, v147
	v_rcp_f32_e32 v161, v167
	v_rcp_f32_e32 v162, v168
	v_rcp_f32_e32 v163, v169
	v_rcp_f32_e32 v164, v170
	v_rcp_f32_e32 v165, v171
	v_rcp_f32_e32 v166, v172
	v_rcp_f32_e32 v167, v173
	v_pk_mul_f32 v[126:127], v[126:127], v[160:161]
	v_pk_mul_f32 v[128:129], v[128:129], v[162:163]
	v_pk_mul_f32 v[118:119], v[118:119], v[164:165]
	v_pk_mul_f32 v[120:121], v[120:121], v[166:167]
	v_pk_mul_f32 v[122:123], v[122:123], v[126:127]
	v_pk_mul_f32 v[124:125], v[124:125], v[128:129]
	v_pk_mul_f32 v[114:115], v[114:115], v[118:119]
	v_pk_mul_f32 v[116:117], v[116:117], v[120:121]
	v_cvt_pk_bf16_f32 v118, v122, v123
	v_cvt_pk_bf16_f32 v119, v124, v125
	v_addc_co_u32_e64 v159, s[0:1], 0, v157, s[0:1]
	v_cvt_pk_bf16_f32 v114, v114, v115
	v_cvt_pk_bf16_f32 v115, v116, v117
	global_store_dwordx2 v[156:157], v[118:119], off nt
	global_store_dwordx2 v[158:159], v[114:115], off nt
	s_add_u32 s0, s13, s24
	s_addc_u32 s1, s34, s25
	v_fmamk_f32 v114, v182, 0x3a800000, v153
	v_mul_f32_e32 v115, 0x4b800000, v114
	v_cmp_gt_f32_e32 vcc, s57, v114
	s_nop 1
	v_cndmask_b32_e32 v114, v114, v115, vcc
	v_rsq_f32_e32 v116, v114
	v_add_u32_e32 v114, 32, v146
	v_ashrrev_i32_e32 v115, 31, v114
	v_lshl_add_u64 v[114:115], v[114:115], 2, s[10:11]
	v_mul_f32_e32 v117, 0x45800000, v116
	v_cndmask_b32_e32 v116, v116, v117, vcc
	v_pk_mul_f32 v[110:111], v[110:111], v[116:117] op_sel_hi:[1,0]
	v_pk_mul_f32 v[112:113], v[112:113], v[116:117] op_sel_hi:[1,0]
	v_pk_mul_f32 v[106:107], v[106:107], v[116:117] op_sel_hi:[1,0]
	v_pk_mul_f32 v[108:109], v[108:109], v[116:117] op_sel_hi:[1,0]
	v_pk_mul_f32 v[102:103], v[102:103], v[116:117] op_sel_hi:[1,0]
	v_pk_mul_f32 v[98:99], v[98:99], v[116:117] op_sel_hi:[1,0]
	v_pk_mul_f32 v[104:105], v[104:105], v[116:117] op_sel_hi:[1,0]
	v_pk_mul_f32 v[100:101], v[100:101], v[116:117] op_sel_hi:[1,0]
	v_mul_f32_e32 v116, 0xbfb8aa3b, v110
	v_mul_f32_e32 v117, 0xbfb8aa3b, v111
	v_mul_f32_e32 v118, 0xbfb8aa3b, v112
	v_mul_f32_e32 v119, 0xbfb8aa3b, v113
	v_mul_f32_e32 v120, 0xbfb8aa3b, v102
	v_mul_f32_e32 v121, 0xbfb8aa3b, v103
	v_mul_f32_e32 v122, 0xbfb8aa3b, v104
	v_mul_f32_e32 v123, 0xbfb8aa3b, v105
	v_exp_f32_e32 v116, v116
	v_exp_f32_e32 v117, v117
	v_exp_f32_e32 v118, v118
	v_exp_f32_e32 v119, v119
	v_exp_f32_e32 v120, v120
	v_exp_f32_e32 v121, v121
	v_exp_f32_e32 v122, v122
	v_exp_f32_e32 v123, v123
	v_add_f32_e32 v116, 1.0, v116
	v_add_f32_e32 v117, 1.0, v117
	v_add_f32_e32 v118, 1.0, v118
	v_add_f32_e32 v119, 1.0, v119
	v_add_f32_e32 v120, 1.0, v120
	v_add_f32_e32 v121, 1.0, v121
	v_add_f32_e32 v122, 1.0, v122
	v_add_f32_e32 v123, 1.0, v123
	v_rcp_f32_e32 v116, v116
	v_rcp_f32_e32 v117, v117
	v_rcp_f32_e32 v118, v118
	v_rcp_f32_e32 v119, v119
	v_rcp_f32_e32 v120, v120
	v_rcp_f32_e32 v121, v121
	v_rcp_f32_e32 v122, v122
	v_rcp_f32_e32 v123, v123
	v_pk_mul_f32 v[110:111], v[110:111], v[116:117]
	v_pk_mul_f32 v[112:113], v[112:113], v[118:119]
	v_pk_mul_f32 v[102:103], v[102:103], v[120:121]
	v_pk_mul_f32 v[104:105], v[104:105], v[122:123]
	v_pk_mul_f32 v[106:107], v[106:107], v[110:111]
	v_pk_mul_f32 v[108:109], v[108:109], v[112:113]
	v_pk_mul_f32 v[98:99], v[98:99], v[102:103]
	v_pk_mul_f32 v[100:101], v[100:101], v[104:105]
	v_cvt_pk_bf16_f32 v102, v106, v107
	v_cvt_pk_bf16_f32 v103, v108, v109
	v_cvt_pk_bf16_f32 v98, v98, v99
	v_cvt_pk_bf16_f32 v99, v100, v101
	global_store_dwordx2 v[156:157], v[102:103], off offset:2048 nt
	global_store_dwordx2 v[158:159], v[98:99], off offset:2048 nt
	v_lshl_add_u64 v[100:101], s[0:1], 0, v[142:143]
	v_add_u32_e32 v98, 48, v146
	v_lshl_add_u64 v[100:101], v[100:101], 0, v[144:145]
	v_ashrrev_i32_e32 v99, 31, v98
	v_lshl_add_u64 v[98:99], v[98:99], 2, s[10:11]
	v_fmamk_f32 v102, v183, 0x3a800000, v153
	v_mul_f32_e32 v103, 0x4b800000, v102
	v_cmp_gt_f32_e32 vcc, s57, v102
	s_nop 1
	v_cndmask_b32_e32 v102, v102, v103, vcc
	v_rsq_f32_e32 v104, v102
	v_add_co_u32_e64 v102, s[0:1], s58, v100
	v_mul_f32_e32 v105, 0x45800000, v104
	v_cndmask_b32_e32 v104, v104, v105, vcc
	v_pk_mul_f32 v[94:95], v[94:95], v[104:105] op_sel_hi:[1,0]
	v_pk_mul_f32 v[96:97], v[96:97], v[104:105] op_sel_hi:[1,0]
	v_pk_mul_f32 v[90:91], v[90:91], v[104:105] op_sel_hi:[1,0]
	v_pk_mul_f32 v[92:93], v[92:93], v[104:105] op_sel_hi:[1,0]
	v_pk_mul_f32 v[86:87], v[86:87], v[104:105] op_sel_hi:[1,0]
	v_pk_mul_f32 v[82:83], v[82:83], v[104:105] op_sel_hi:[1,0]
	v_pk_mul_f32 v[88:89], v[88:89], v[104:105] op_sel_hi:[1,0]
	v_pk_mul_f32 v[84:85], v[84:85], v[104:105] op_sel_hi:[1,0]
	v_mul_f32_e32 v104, 0xbfb8aa3b, v94
	v_mul_f32_e32 v105, 0xbfb8aa3b, v95
	v_mul_f32_e32 v106, 0xbfb8aa3b, v96
	v_mul_f32_e32 v107, 0xbfb8aa3b, v97
	v_mul_f32_e32 v108, 0xbfb8aa3b, v86
	v_mul_f32_e32 v109, 0xbfb8aa3b, v87
	v_mul_f32_e32 v110, 0xbfb8aa3b, v88
	v_mul_f32_e32 v111, 0xbfb8aa3b, v89
	v_exp_f32_e32 v104, v104
	v_exp_f32_e32 v105, v105
	v_exp_f32_e32 v106, v106
	v_exp_f32_e32 v107, v107
	v_exp_f32_e32 v108, v108
	v_exp_f32_e32 v109, v109
	v_exp_f32_e32 v110, v110
	v_exp_f32_e32 v111, v111
	v_add_f32_e32 v104, 1.0, v104
	v_add_f32_e32 v105, 1.0, v105
	v_add_f32_e32 v106, 1.0, v106
	v_add_f32_e32 v107, 1.0, v107
	v_add_f32_e32 v108, 1.0, v108
	v_add_f32_e32 v109, 1.0, v109
	v_add_f32_e32 v110, 1.0, v110
	v_add_f32_e32 v111, 1.0, v111
	v_rcp_f32_e32 v104, v104
	v_rcp_f32_e32 v105, v105
	v_rcp_f32_e32 v106, v106
	v_rcp_f32_e32 v107, v107
	v_rcp_f32_e32 v108, v108
	v_rcp_f32_e32 v109, v109
	v_rcp_f32_e32 v110, v110
	v_rcp_f32_e32 v111, v111
	v_pk_mul_f32 v[94:95], v[94:95], v[104:105]
	v_pk_mul_f32 v[96:97], v[96:97], v[106:107]
	v_pk_mul_f32 v[86:87], v[86:87], v[108:109]
	v_pk_mul_f32 v[88:89], v[88:89], v[110:111]
	v_pk_mul_f32 v[90:91], v[90:91], v[94:95]
	v_pk_mul_f32 v[92:93], v[92:93], v[96:97]
	v_pk_mul_f32 v[82:83], v[82:83], v[86:87]
	v_pk_mul_f32 v[84:85], v[84:85], v[88:89]
	v_cvt_pk_bf16_f32 v86, v90, v91
	v_cvt_pk_bf16_f32 v87, v92, v93
	v_addc_co_u32_e64 v103, s[0:1], 0, v101, s[0:1]
	v_cvt_pk_bf16_f32 v82, v82, v83
	v_cvt_pk_bf16_f32 v83, v84, v85
	global_store_dwordx2 v[100:101], v[86:87], off nt
	global_store_dwordx2 v[102:103], v[82:83], off nt
	s_add_u32 s0, s13, s26
	s_addc_u32 s1, s34, s27
	v_lshl_add_u64 v[84:85], s[0:1], 0, v[142:143]
	v_add_u32_e32 v82, 0x80, v146
	v_lshl_add_u64 v[84:85], v[84:85], 0, v[144:145]
	v_ashrrev_i32_e32 v83, 31, v82
	v_lshl_add_u64 v[82:83], v[82:83], 2, s[10:11]
	v_fmamk_f32 v86, v184, 0x3a800000, v153
	v_mul_f32_e32 v87, 0x4b800000, v86
	v_cmp_gt_f32_e32 vcc, s57, v86
	s_nop 1
	v_cndmask_b32_e32 v86, v86, v87, vcc
	v_rsq_f32_e32 v88, v86
	v_add_co_u32_e64 v86, s[0:1], s58, v84
	v_mul_f32_e32 v89, 0x45800000, v88
	v_cndmask_b32_e32 v88, v88, v89, vcc
	v_pk_mul_f32 v[78:79], v[78:79], v[88:89] op_sel_hi:[1,0]
	v_pk_mul_f32 v[80:81], v[80:81], v[88:89] op_sel_hi:[1,0]
	v_pk_mul_f32 v[74:75], v[74:75], v[88:89] op_sel_hi:[1,0]
	v_pk_mul_f32 v[76:77], v[76:77], v[88:89] op_sel_hi:[1,0]
	v_pk_mul_f32 v[70:71], v[70:71], v[88:89] op_sel_hi:[1,0]
	v_pk_mul_f32 v[66:67], v[66:67], v[88:89] op_sel_hi:[1,0]
	v_pk_mul_f32 v[72:73], v[72:73], v[88:89] op_sel_hi:[1,0]
	v_pk_mul_f32 v[68:69], v[68:69], v[88:89] op_sel_hi:[1,0]
	v_mul_f32_e32 v88, 0xbfb8aa3b, v78
	v_mul_f32_e32 v89, 0xbfb8aa3b, v79
	v_mul_f32_e32 v90, 0xbfb8aa3b, v80
	v_mul_f32_e32 v91, 0xbfb8aa3b, v81
	v_mul_f32_e32 v92, 0xbfb8aa3b, v70
	v_mul_f32_e32 v93, 0xbfb8aa3b, v71
	v_mul_f32_e32 v94, 0xbfb8aa3b, v72
	v_mul_f32_e32 v95, 0xbfb8aa3b, v73
	v_exp_f32_e32 v88, v88
	v_exp_f32_e32 v89, v89
	v_exp_f32_e32 v90, v90
	v_exp_f32_e32 v91, v91
	v_exp_f32_e32 v92, v92
	v_exp_f32_e32 v93, v93
	v_exp_f32_e32 v94, v94
	v_exp_f32_e32 v95, v95
	v_add_f32_e32 v88, 1.0, v88
	v_add_f32_e32 v89, 1.0, v89
	v_add_f32_e32 v90, 1.0, v90
	v_add_f32_e32 v91, 1.0, v91
	v_add_f32_e32 v92, 1.0, v92
	v_add_f32_e32 v93, 1.0, v93
	v_add_f32_e32 v94, 1.0, v94
	v_add_f32_e32 v95, 1.0, v95
	v_rcp_f32_e32 v88, v88
	v_rcp_f32_e32 v89, v89
	v_rcp_f32_e32 v90, v90
	v_rcp_f32_e32 v91, v91
	v_rcp_f32_e32 v92, v92
	v_rcp_f32_e32 v93, v93
	v_rcp_f32_e32 v94, v94
	v_rcp_f32_e32 v95, v95
	v_pk_mul_f32 v[78:79], v[78:79], v[88:89]
	v_pk_mul_f32 v[80:81], v[80:81], v[90:91]
	v_pk_mul_f32 v[70:71], v[70:71], v[92:93]
	v_pk_mul_f32 v[72:73], v[72:73], v[94:95]
	v_pk_mul_f32 v[74:75], v[74:75], v[78:79]
	v_pk_mul_f32 v[76:77], v[76:77], v[80:81]
	v_pk_mul_f32 v[66:67], v[66:67], v[70:71]
	v_pk_mul_f32 v[68:69], v[68:69], v[72:73]
	v_cvt_pk_bf16_f32 v70, v74, v75
	v_cvt_pk_bf16_f32 v71, v76, v77
	v_addc_co_u32_e64 v87, s[0:1], 0, v85, s[0:1]
	v_cvt_pk_bf16_f32 v66, v66, v67
	v_cvt_pk_bf16_f32 v67, v68, v69
	global_store_dwordx2 v[84:85], v[70:71], off nt
	global_store_dwordx2 v[86:87], v[66:67], off nt
	s_or_b32 s0, s12, 1
	s_ashr_i32 s1, s0, 31
	s_lshl_b64 s[0:1], s[0:1], 14
	s_add_u32 s12, s29, s0
	s_addc_u32 s13, s31, s1
	s_add_u32 s0, s12, s22
	s_addc_u32 s1, s13, s23
	v_lshl_add_u64 v[68:69], s[0:1], 0, v[142:143]
	v_add_u32_e32 v66, 0x90, v146
	v_lshl_add_u64 v[68:69], v[68:69], 0, v[144:145]
	v_ashrrev_i32_e32 v67, 31, v66
	v_lshl_add_u64 v[66:67], v[66:67], 2, s[10:11]
	v_fmamk_f32 v70, v185, 0x3a800000, v153
	v_mul_f32_e32 v71, 0x4b800000, v70
	v_cmp_gt_f32_e32 vcc, s57, v70
	s_nop 1
	v_cndmask_b32_e32 v70, v70, v71, vcc
	v_rsq_f32_e32 v72, v70
	v_add_co_u32_e64 v70, s[0:1], s58, v68
	v_mul_f32_e32 v73, 0x45800000, v72
	v_cndmask_b32_e32 v72, v72, v73, vcc
	v_pk_mul_f32 v[62:63], v[62:63], v[72:73] op_sel_hi:[1,0]
	v_pk_mul_f32 v[64:65], v[64:65], v[72:73] op_sel_hi:[1,0]
	v_pk_mul_f32 v[58:59], v[58:59], v[72:73] op_sel_hi:[1,0]
	v_pk_mul_f32 v[60:61], v[60:61], v[72:73] op_sel_hi:[1,0]
	v_pk_mul_f32 v[54:55], v[54:55], v[72:73] op_sel_hi:[1,0]
	v_pk_mul_f32 v[50:51], v[50:51], v[72:73] op_sel_hi:[1,0]
	v_pk_mul_f32 v[56:57], v[56:57], v[72:73] op_sel_hi:[1,0]
	v_pk_mul_f32 v[52:53], v[52:53], v[72:73] op_sel_hi:[1,0]
	v_mul_f32_e32 v72, 0xbfb8aa3b, v62
	v_mul_f32_e32 v73, 0xbfb8aa3b, v63
	v_mul_f32_e32 v74, 0xbfb8aa3b, v64
	v_mul_f32_e32 v75, 0xbfb8aa3b, v65
	v_mul_f32_e32 v76, 0xbfb8aa3b, v54
	v_mul_f32_e32 v77, 0xbfb8aa3b, v55
	v_mul_f32_e32 v78, 0xbfb8aa3b, v56
	v_mul_f32_e32 v79, 0xbfb8aa3b, v57
	v_exp_f32_e32 v72, v72
	v_exp_f32_e32 v73, v73
	v_exp_f32_e32 v74, v74
	v_exp_f32_e32 v75, v75
	v_exp_f32_e32 v76, v76
	v_exp_f32_e32 v77, v77
	v_exp_f32_e32 v78, v78
	v_exp_f32_e32 v79, v79
	v_add_f32_e32 v72, 1.0, v72
	v_add_f32_e32 v73, 1.0, v73
	v_add_f32_e32 v74, 1.0, v74
	v_add_f32_e32 v75, 1.0, v75
	v_add_f32_e32 v76, 1.0, v76
	v_add_f32_e32 v77, 1.0, v77
	v_add_f32_e32 v78, 1.0, v78
	v_add_f32_e32 v79, 1.0, v79
	v_rcp_f32_e32 v72, v72
	v_rcp_f32_e32 v73, v73
	v_rcp_f32_e32 v74, v74
	v_rcp_f32_e32 v75, v75
	v_rcp_f32_e32 v76, v76
	v_rcp_f32_e32 v77, v77
	v_rcp_f32_e32 v78, v78
	v_rcp_f32_e32 v79, v79
	v_pk_mul_f32 v[62:63], v[62:63], v[72:73]
	v_pk_mul_f32 v[64:65], v[64:65], v[74:75]
	v_pk_mul_f32 v[54:55], v[54:55], v[76:77]
	v_pk_mul_f32 v[56:57], v[56:57], v[78:79]
	v_pk_mul_f32 v[58:59], v[58:59], v[62:63]
	v_pk_mul_f32 v[60:61], v[60:61], v[64:65]
	v_pk_mul_f32 v[50:51], v[50:51], v[54:55]
	v_pk_mul_f32 v[52:53], v[52:53], v[56:57]
	v_cvt_pk_bf16_f32 v54, v58, v59
	v_cvt_pk_bf16_f32 v55, v60, v61
	v_addc_co_u32_e64 v71, s[0:1], 0, v69, s[0:1]
	v_cvt_pk_bf16_f32 v50, v50, v51
	v_cvt_pk_bf16_f32 v51, v52, v53
	global_store_dwordx2 v[68:69], v[54:55], off nt
	global_store_dwordx2 v[70:71], v[50:51], off nt
	s_add_u32 s0, s12, s24
	s_addc_u32 s1, s13, s25
	v_fmamk_f32 v50, v186, 0x3a800000, v153
	v_mul_f32_e32 v51, 0x4b800000, v50
	v_cmp_gt_f32_e32 vcc, s57, v50
	s_nop 1
	v_cndmask_b32_e32 v50, v50, v51, vcc
	v_rsq_f32_e32 v52, v50
	v_add_u32_e32 v50, 0xa0, v146
	v_ashrrev_i32_e32 v51, 31, v50
	v_lshl_add_u64 v[50:51], v[50:51], 2, s[10:11]
	v_mul_f32_e32 v53, 0x45800000, v52
	v_cndmask_b32_e32 v52, v52, v53, vcc
	v_pk_mul_f32 v[46:47], v[46:47], v[52:53] op_sel_hi:[1,0]
	v_pk_mul_f32 v[48:49], v[48:49], v[52:53] op_sel_hi:[1,0]
	v_pk_mul_f32 v[42:43], v[42:43], v[52:53] op_sel_hi:[1,0]
	v_pk_mul_f32 v[44:45], v[44:45], v[52:53] op_sel_hi:[1,0]
	v_pk_mul_f32 v[38:39], v[38:39], v[52:53] op_sel_hi:[1,0]
	v_pk_mul_f32 v[34:35], v[34:35], v[52:53] op_sel_hi:[1,0]
	v_pk_mul_f32 v[40:41], v[40:41], v[52:53] op_sel_hi:[1,0]
	v_pk_mul_f32 v[36:37], v[36:37], v[52:53] op_sel_hi:[1,0]
	v_mul_f32_e32 v52, 0xbfb8aa3b, v46
	v_mul_f32_e32 v53, 0xbfb8aa3b, v47
	v_mul_f32_e32 v54, 0xbfb8aa3b, v48
	v_mul_f32_e32 v55, 0xbfb8aa3b, v49
	v_mul_f32_e32 v56, 0xbfb8aa3b, v38
	v_mul_f32_e32 v57, 0xbfb8aa3b, v39
	v_mul_f32_e32 v58, 0xbfb8aa3b, v40
	v_mul_f32_e32 v59, 0xbfb8aa3b, v41
	v_exp_f32_e32 v52, v52
	v_exp_f32_e32 v53, v53
	v_exp_f32_e32 v54, v54
	v_exp_f32_e32 v55, v55
	v_exp_f32_e32 v56, v56
	v_exp_f32_e32 v57, v57
	v_exp_f32_e32 v58, v58
	v_exp_f32_e32 v59, v59
	v_add_f32_e32 v52, 1.0, v52
	v_add_f32_e32 v53, 1.0, v53
	v_add_f32_e32 v54, 1.0, v54
	v_add_f32_e32 v55, 1.0, v55
	v_add_f32_e32 v56, 1.0, v56
	v_add_f32_e32 v57, 1.0, v57
	v_add_f32_e32 v58, 1.0, v58
	v_add_f32_e32 v59, 1.0, v59
	v_rcp_f32_e32 v52, v52
	v_rcp_f32_e32 v53, v53
	v_rcp_f32_e32 v54, v54
	v_rcp_f32_e32 v55, v55
	v_rcp_f32_e32 v56, v56
	v_rcp_f32_e32 v57, v57
	v_rcp_f32_e32 v58, v58
	v_rcp_f32_e32 v59, v59
	v_pk_mul_f32 v[46:47], v[46:47], v[52:53]
	v_pk_mul_f32 v[48:49], v[48:49], v[54:55]
	v_pk_mul_f32 v[38:39], v[38:39], v[56:57]
	v_pk_mul_f32 v[40:41], v[40:41], v[58:59]
	v_pk_mul_f32 v[42:43], v[42:43], v[46:47]
	v_pk_mul_f32 v[44:45], v[44:45], v[48:49]
	v_pk_mul_f32 v[34:35], v[34:35], v[38:39]
	v_pk_mul_f32 v[36:37], v[36:37], v[40:41]
	v_cvt_pk_bf16_f32 v38, v42, v43
	v_cvt_pk_bf16_f32 v39, v44, v45
	v_cvt_pk_bf16_f32 v34, v34, v35
	v_cvt_pk_bf16_f32 v35, v36, v37
	global_store_dwordx2 v[68:69], v[38:39], off offset:2048 nt
	global_store_dwordx2 v[70:71], v[34:35], off offset:2048 nt
	v_lshl_add_u64 v[36:37], s[0:1], 0, v[142:143]
	v_add_u32_e32 v34, 0xb0, v146
	v_lshl_add_u64 v[36:37], v[36:37], 0, v[144:145]
	v_ashrrev_i32_e32 v35, 31, v34
	v_lshl_add_u64 v[34:35], v[34:35], 2, s[10:11]
	v_fmamk_f32 v38, v187, 0x3a800000, v153
	v_mul_f32_e32 v39, 0x4b800000, v38
	v_cmp_gt_f32_e32 vcc, s57, v38
	s_nop 1
	v_cndmask_b32_e32 v38, v38, v39, vcc
	v_rsq_f32_e32 v40, v38
	v_add_co_u32_e64 v38, s[0:1], s58, v36
	v_mul_f32_e32 v41, 0x45800000, v40
	v_cndmask_b32_e32 v40, v40, v41, vcc
	v_pk_mul_f32 v[30:31], v[30:31], v[40:41] op_sel_hi:[1,0]
	v_pk_mul_f32 v[32:33], v[32:33], v[40:41] op_sel_hi:[1,0]
	v_pk_mul_f32 v[26:27], v[26:27], v[40:41] op_sel_hi:[1,0]
	v_pk_mul_f32 v[28:29], v[28:29], v[40:41] op_sel_hi:[1,0]
	v_pk_mul_f32 v[22:23], v[22:23], v[40:41] op_sel_hi:[1,0]
	v_pk_mul_f32 v[18:19], v[18:19], v[40:41] op_sel_hi:[1,0]
	v_pk_mul_f32 v[24:25], v[24:25], v[40:41] op_sel_hi:[1,0]
	v_pk_mul_f32 v[20:21], v[20:21], v[40:41] op_sel_hi:[1,0]
	v_mul_f32_e32 v40, 0xbfb8aa3b, v30
	v_mul_f32_e32 v41, 0xbfb8aa3b, v31
	v_mul_f32_e32 v42, 0xbfb8aa3b, v32
	v_mul_f32_e32 v43, 0xbfb8aa3b, v33
	v_mul_f32_e32 v44, 0xbfb8aa3b, v22
	v_mul_f32_e32 v45, 0xbfb8aa3b, v23
	v_mul_f32_e32 v46, 0xbfb8aa3b, v24
	v_mul_f32_e32 v47, 0xbfb8aa3b, v25
	v_exp_f32_e32 v40, v40
	v_exp_f32_e32 v41, v41
	v_exp_f32_e32 v42, v42
	v_exp_f32_e32 v43, v43
	v_exp_f32_e32 v44, v44
	v_exp_f32_e32 v45, v45
	v_exp_f32_e32 v46, v46
	v_exp_f32_e32 v47, v47
	v_add_f32_e32 v40, 1.0, v40
	v_add_f32_e32 v41, 1.0, v41
	v_add_f32_e32 v42, 1.0, v42
	v_add_f32_e32 v43, 1.0, v43
	v_add_f32_e32 v44, 1.0, v44
	v_add_f32_e32 v45, 1.0, v45
	v_add_f32_e32 v46, 1.0, v46
	v_add_f32_e32 v47, 1.0, v47
	v_rcp_f32_e32 v40, v40
	v_rcp_f32_e32 v41, v41
	v_rcp_f32_e32 v42, v42
	v_rcp_f32_e32 v43, v43
	v_rcp_f32_e32 v44, v44
	v_rcp_f32_e32 v45, v45
	v_rcp_f32_e32 v46, v46
	v_rcp_f32_e32 v47, v47
	v_pk_mul_f32 v[30:31], v[30:31], v[40:41]
	v_pk_mul_f32 v[32:33], v[32:33], v[42:43]
	v_pk_mul_f32 v[22:23], v[22:23], v[44:45]
	v_pk_mul_f32 v[24:25], v[24:25], v[46:47]
	v_pk_mul_f32 v[26:27], v[26:27], v[30:31]
	v_pk_mul_f32 v[28:29], v[28:29], v[32:33]
	v_pk_mul_f32 v[18:19], v[18:19], v[22:23]
	v_pk_mul_f32 v[20:21], v[20:21], v[24:25]
	v_cvt_pk_bf16_f32 v22, v26, v27
	v_cvt_pk_bf16_f32 v23, v28, v29
	v_addc_co_u32_e64 v39, s[0:1], 0, v37, s[0:1]
	v_cvt_pk_bf16_f32 v18, v18, v19
	v_cvt_pk_bf16_f32 v19, v20, v21
	global_store_dwordx2 v[36:37], v[22:23], off nt
	global_store_dwordx2 v[38:39], v[18:19], off nt
	s_add_u32 s0, s12, s26
	s_addc_u32 s1, s13, s27
	v_lshl_add_u64 v[18:19], s[0:1], 0, v[142:143]
	v_lshl_add_u64 v[18:19], v[18:19], 0, v[144:145]
	v_add_co_u32_e32 v20, vcc, 0x400000, v18
	v_fmamk_f32 v21, v188, 0x3a800000, v153
	v_mul_f32_e32 v22, 0x4b800000, v21
	v_cmp_gt_f32_e64 s[0:1], s57, v21
	s_nop 1
	v_cndmask_b32_e64 v21, v21, v22, s[0:1]
	v_rsq_f32_e32 v22, v21
	v_addc_co_u32_e32 v21, vcc, 0, v19, vcc
	s_andn2_b64 vcc, exec, s[6:7]
	v_mul_f32_e32 v23, 0x45800000, v22
	v_cndmask_b32_e64 v22, v22, v23, s[0:1]
	v_pk_mul_f32 v[14:15], v[14:15], v[22:23] op_sel_hi:[1,0]
	v_pk_mul_f32 v[16:17], v[16:17], v[22:23] op_sel_hi:[1,0]
	v_pk_mul_f32 v[10:11], v[10:11], v[22:23] op_sel_hi:[1,0]
	v_pk_mul_f32 v[12:13], v[12:13], v[22:23] op_sel_hi:[1,0]
	v_pk_mul_f32 v[6:7], v[6:7], v[22:23] op_sel_hi:[1,0]
	v_pk_mul_f32 v[2:3], v[2:3], v[22:23] op_sel_hi:[1,0]
	v_pk_mul_f32 v[8:9], v[8:9], v[22:23] op_sel_hi:[1,0]
	v_pk_mul_f32 v[4:5], v[4:5], v[22:23] op_sel_hi:[1,0]
	v_mul_f32_e32 v22, 0xbfb8aa3b, v14
	v_mul_f32_e32 v23, 0xbfb8aa3b, v15
	v_mul_f32_e32 v24, 0xbfb8aa3b, v16
	v_mul_f32_e32 v25, 0xbfb8aa3b, v17
	v_mul_f32_e32 v26, 0xbfb8aa3b, v6
	v_mul_f32_e32 v27, 0xbfb8aa3b, v7
	v_mul_f32_e32 v28, 0xbfb8aa3b, v8
	v_mul_f32_e32 v29, 0xbfb8aa3b, v9
	v_exp_f32_e32 v22, v22
	v_exp_f32_e32 v23, v23
	v_exp_f32_e32 v24, v24
	v_exp_f32_e32 v25, v25
	v_exp_f32_e32 v26, v26
	v_exp_f32_e32 v27, v27
	v_exp_f32_e32 v28, v28
	v_exp_f32_e32 v29, v29
	v_add_f32_e32 v22, 1.0, v22
	v_add_f32_e32 v23, 1.0, v23
	v_add_f32_e32 v24, 1.0, v24
	v_add_f32_e32 v25, 1.0, v25
	v_add_f32_e32 v26, 1.0, v26
	v_add_f32_e32 v27, 1.0, v27
	v_add_f32_e32 v28, 1.0, v28
	v_add_f32_e32 v29, 1.0, v29
	v_rcp_f32_e32 v22, v22
	v_rcp_f32_e32 v23, v23
	v_rcp_f32_e32 v24, v24
	v_rcp_f32_e32 v25, v25
	v_rcp_f32_e32 v26, v26
	v_rcp_f32_e32 v27, v27
	v_rcp_f32_e32 v28, v28
	v_rcp_f32_e32 v29, v29
	v_pk_mul_f32 v[14:15], v[14:15], v[22:23]
	v_pk_mul_f32 v[16:17], v[16:17], v[24:25]
	v_pk_mul_f32 v[6:7], v[6:7], v[26:27]
	v_pk_mul_f32 v[8:9], v[8:9], v[28:29]
	v_pk_mul_f32 v[10:11], v[10:11], v[14:15]
	v_pk_mul_f32 v[12:13], v[12:13], v[16:17]
	v_pk_mul_f32 v[2:3], v[2:3], v[6:7]
	v_pk_mul_f32 v[4:5], v[4:5], v[8:9]
	v_cvt_pk_bf16_f32 v6, v10, v11
	v_cvt_pk_bf16_f32 v7, v12, v13
	s_mov_b64 s[0:1], -1
	v_cvt_pk_bf16_f32 v2, v2, v3
	v_cvt_pk_bf16_f32 v3, v4, v5
	global_store_dwordx2 v[18:19], v[6:7], off nt
	global_store_dwordx2 v[20:21], v[2:3], off nt
	s_cbranch_vccnz .LBB0_1385
	s_andn2_b64 vcc, exec, s[14:15]
	s_cbranch_vccnz .LBB0_1384
	s_barrier
	s_branch .LBB0_1384
